# baseline (speedup 1.0000x reference)
.LBB0_546:
	s_waitcnt vmcnt(7)
	ds_write_b128 v0, v[66:69] offset:18432
	s_waitcnt vmcnt(6)
	ds_write_b128 v0, v[78:81] offset:23040
	s_add_i32 s12, s1, 2
	s_sub_i32 s13, s0, 64
	ds_read_b128 v[66:69], v114
	ds_read_b128 v[78:81], v115 offset:36864
	ds_read_b128 v[118:121], v114 offset:4608
	ds_read_b128 v[122:125], v115 offset:41472
	s_cmp_lt_u32 s1, 14
	s_cselect_b64 s[14:15], -1, 0
	s_and_b64 vcc, s[14:15], exec
	s_cselect_b32 s16, s13, 0
	s_lshl_b64 s[14:15], s[16:17], 1
	s_waitcnt lgkmcnt(2)
	v_mfma_f32_32x32x16_bf16 v[50:65], v[66:69], v[78:81], v[50:65]
	v_lshl_add_u64 v[126:127], v[102:103], 0, s[14:15]
	s_waitcnt lgkmcnt(0)
	v_mfma_f32_32x32x16_bf16 v[34:49], v[66:69], v[122:125], v[34:49]
	v_lshl_add_u64 v[66:67], v[98:99], 0, s[14:15]
	v_mfma_f32_32x32x16_bf16 v[18:33], v[118:121], v[78:81], v[18:33]
	global_load_dwordx4 v[66:69], v[66:67], off
	s_nop 0
	global_load_dwordx4 v[78:81], v[126:127], off
	v_mfma_f32_32x32x16_bf16 v[2:17], v[118:121], v[122:125], v[2:17]
	s_waitcnt vmcnt(7)
	ds_write_b128 v0, v[70:73] offset:27648
	s_waitcnt vmcnt(5)
	ds_write_b128 v0, v[82:85] offset:32256
	ds_read_b128 v[70:73], v114 offset:32
	ds_read_b128 v[82:85], v115 offset:36896
	ds_read_b128 v[118:121], v114 offset:4640
	ds_read_b128 v[122:125], v115 offset:41504
	v_lshl_add_u64 v[126:127], v[106:107], 0, s[14:15]
	s_waitcnt lgkmcnt(2)
	v_mfma_f32_32x32x16_bf16 v[50:65], v[70:73], v[82:85], v[50:65]
	s_waitcnt lgkmcnt(0)
	v_mfma_f32_32x32x16_bf16 v[34:49], v[70:73], v[122:125], v[34:49]
	v_lshl_add_u64 v[70:71], v[104:105], 0, s[14:15]
	v_mfma_f32_32x32x16_bf16 v[18:33], v[118:121], v[82:85], v[18:33]
	global_load_dwordx4 v[70:73], v[70:71], off
	s_nop 0
	global_load_dwordx4 v[82:85], v[126:127], off
	v_mfma_f32_32x32x16_bf16 v[2:17], v[118:121], v[122:125], v[2:17]
	ds_write_b128 v0, v[74:77] offset:55296
	s_waitcnt vmcnt(6)
	ds_write_b128 v0, v[86:89] offset:59904
	ds_read_b128 v[74:77], v114 offset:64
	ds_read_b128 v[86:89], v115 offset:36928
	ds_read_b128 v[118:121], v114 offset:4672
	ds_read_b128 v[122:125], v115 offset:41536
	v_lshl_add_u64 v[126:127], v[108:109], 0, s[14:15]
	s_waitcnt lgkmcnt(2)
	v_mfma_f32_32x32x16_bf16 v[50:65], v[74:77], v[86:89], v[50:65]
	s_waitcnt lgkmcnt(0)
	v_mfma_f32_32x32x16_bf16 v[34:49], v[74:77], v[122:125], v[34:49]
	v_lshl_add_u64 v[74:75], v[100:101], 0, s[14:15]
	v_mfma_f32_32x32x16_bf16 v[18:33], v[118:121], v[86:89], v[18:33]
	global_load_dwordx4 v[74:77], v[74:75], off
	s_nop 0
	global_load_dwordx4 v[86:89], v[126:127], off
	v_mfma_f32_32x32x16_bf16 v[2:17], v[118:121], v[122:125], v[2:17]
	s_waitcnt vmcnt(7)
	ds_write_b128 v0, v[90:93] offset:64512
	s_waitcnt vmcnt(6)
	ds_write_b128 v117, v[94:97] offset:13824
	ds_read_b128 v[90:93], v114 offset:96
	ds_read_b128 v[94:97], v115 offset:36960
	ds_read_b128 v[118:121], v114 offset:4704
	ds_read_b128 v[122:125], v115 offset:41568
	v_lshl_add_u64 v[126:127], v[112:113], 0, s[14:15]
	s_waitcnt lgkmcnt(2)
	v_mfma_f32_32x32x16_bf16 v[50:65], v[90:93], v[94:97], v[50:65]
	s_waitcnt lgkmcnt(0)
	v_mfma_f32_32x32x16_bf16 v[34:49], v[90:93], v[122:125], v[34:49]
	v_lshl_add_u64 v[90:91], v[110:111], 0, s[14:15]
	v_mfma_f32_32x32x16_bf16 v[18:33], v[118:121], v[94:97], v[18:33]
	global_load_dwordx4 v[90:93], v[90:91], off
	s_nop 0
	global_load_dwordx4 v[94:97], v[126:127], off
	v_mfma_f32_32x32x16_bf16 v[2:17], v[118:121], v[122:125], v[2:17]
	s_barrier
	s_waitcnt vmcnt(7)
	ds_write_b128 v0, v[66:69]
	s_waitcnt vmcnt(6)
	ds_write_b128 v0, v[78:81] offset:4608
	ds_read_b128 v[66:69], v114 offset:18432
	ds_read_b128 v[78:81], v115 offset:55296
	ds_read_b128 v[118:121], v114 offset:23040
	ds_read_b128 v[122:125], v115 offset:59904
	s_cmp_lt_u32 s1, 13
	s_cselect_b32 s16, s0, 0
	s_lshl_b64 s[14:15], s[16:17], 1
	s_waitcnt lgkmcnt(2)
	v_mfma_f32_32x32x16_bf16 v[50:65], v[66:69], v[78:81], v[50:65]
	v_lshl_add_u64 v[126:127], v[102:103], 0, s[14:15]
	s_waitcnt lgkmcnt(0)
	v_mfma_f32_32x32x16_bf16 v[34:49], v[66:69], v[122:125], v[34:49]
	v_lshl_add_u64 v[66:67], v[98:99], 0, s[14:15]
	v_mfma_f32_32x32x16_bf16 v[18:33], v[118:121], v[78:81], v[18:33]
	global_load_dwordx4 v[66:69], v[66:67], off
	s_nop 0
	global_load_dwordx4 v[78:81], v[126:127], off
	v_mfma_f32_32x32x16_bf16 v[2:17], v[118:121], v[122:125], v[2:17]
	s_waitcnt vmcnt(7)
	ds_write_b128 v0, v[70:73] offset:9216
	s_waitcnt vmcnt(6)
	ds_write_b128 v0, v[82:85] offset:13824
	ds_read_b128 v[70:73], v114 offset:18464
	ds_read_b128 v[82:85], v115 offset:55328
	ds_read_b128 v[118:121], v114 offset:23072
	ds_read_b128 v[122:125], v115 offset:59936
	v_lshl_add_u64 v[126:127], v[106:107], 0, s[14:15]
	s_waitcnt lgkmcnt(2)
	v_mfma_f32_32x32x16_bf16 v[50:65], v[70:73], v[82:85], v[50:65]
	s_waitcnt lgkmcnt(0)
	v_mfma_f32_32x32x16_bf16 v[34:49], v[70:73], v[122:125], v[34:49]
	v_lshl_add_u64 v[70:71], v[104:105], 0, s[14:15]
	v_mfma_f32_32x32x16_bf16 v[18:33], v[118:121], v[82:85], v[18:33]
	global_load_dwordx4 v[70:73], v[70:71], off
	s_nop 0
	global_load_dwordx4 v[82:85], v[126:127], off
	v_mfma_f32_32x32x16_bf16 v[2:17], v[118:121], v[122:125], v[2:17]
	s_waitcnt vmcnt(7)
	ds_write_b128 v0, v[74:77] offset:36864
	s_waitcnt vmcnt(6)
	ds_write_b128 v0, v[86:89] offset:41472
	ds_read_b128 v[74:77], v114 offset:18496
	ds_read_b128 v[86:89], v115 offset:55360
	ds_read_b128 v[118:121], v114 offset:23104
	ds_read_b128 v[122:125], v115 offset:59968
	v_lshl_add_u64 v[126:127], v[108:109], 0, s[14:15]
	s_waitcnt lgkmcnt(2)
	v_mfma_f32_32x32x16_bf16 v[50:65], v[74:77], v[86:89], v[50:65]
	s_waitcnt lgkmcnt(0)
	v_mfma_f32_32x32x16_bf16 v[34:49], v[74:77], v[122:125], v[34:49]
	v_lshl_add_u64 v[74:75], v[100:101], 0, s[14:15]
	v_mfma_f32_32x32x16_bf16 v[18:33], v[118:121], v[86:89], v[18:33]
	global_load_dwordx4 v[74:77], v[74:75], off
	s_nop 0
	global_load_dwordx4 v[86:89], v[126:127], off
	v_mfma_f32_32x32x16_bf16 v[2:17], v[118:121], v[122:125], v[2:17]
	s_waitcnt vmcnt(7)
	ds_write_b128 v0, v[90:93] offset:46080
	s_waitcnt vmcnt(6)
	ds_write_b128 v0, v[94:97] offset:50688
	ds_read_b128 v[90:93], v114 offset:18528
	ds_read_b128 v[94:97], v115 offset:55392
	ds_read_b128 v[118:121], v114 offset:23136
	ds_read_b128 v[122:125], v115 offset:60000
	v_lshl_add_u64 v[126:127], v[112:113], 0, s[14:15]
	s_waitcnt lgkmcnt(2)
	v_mfma_f32_32x32x16_bf16 v[50:65], v[90:93], v[94:97], v[50:65]
	s_waitcnt lgkmcnt(0)
	v_mfma_f32_32x32x16_bf16 v[34:49], v[90:93], v[122:125], v[34:49]
	v_lshl_add_u64 v[90:91], v[110:111], 0, s[14:15]
	v_mfma_f32_32x32x16_bf16 v[18:33], v[118:121], v[94:97], v[18:33]
	global_load_dwordx4 v[90:93], v[90:91], off
	s_nop 0
	global_load_dwordx4 v[94:97], v[126:127], off
	v_mfma_f32_32x32x16_bf16 v[2:17], v[118:121], v[122:125], v[2:17]
	s_addk_i32 s0, 0x80
	s_mov_b32 s1, s12
	s_barrier
	s_cbranch_vccnz .LBB0_546
	s_and_saveexec_b64 s[0:1], s[38:39]
	s_cbranch_execz .LBB0_544
	s_and_b32 s12, s11, 64
	v_and_or_b32 v0, v116, 31, s12
	s_waitcnt vmcnt(7)
	v_or_b32_e32 v68, s9, v0
	s_ashr_i32 s9, s11, 1
	s_lshl_b32 s10, s10, 7
	s_andn2_b32 s9, s9, 63
	s_add_i32 s9, s9, s10
	v_lshrrev_b32_e32 v0, 3, v116
	v_ashrrev_i32_e32 v69, 31, v68
	s_waitcnt vmcnt(5)
	v_and_or_b32 v70, v0, 4, s9
	v_lshlrev_b64 v[66:67], 11, v[68:69]
	v_ashrrev_i32_e32 v71, 31, v70
	v_lshl_add_u64 v[66:67], s[4:5], 0, v[66:67]
	v_lshlrev_b64 v[70:71], 1, v[70:71]
	v_lshl_add_u64 v[66:67], v[66:67], 0, v[70:71]
	v_or_b32_e32 v242, 32, v68
	v_ashrrev_i32_e32 v243, 31, v242
	v_lshlrev_b64 v[242:243], 11, v[242:243]
	v_lshl_add_u64 v[242:243], s[4:5], 0, v[242:243]
	v_lshl_add_u64 v[242:243], v[242:243], 0, v[70:71]
	global_load_dwordx2 v[210:211], v[66:67], off
	global_load_dwordx2 v[212:213], v[66:67], off offset:16
	global_load_dwordx2 v[214:215], v[66:67], off offset:32
	global_load_dwordx2 v[216:217], v[66:67], off offset:48
	global_load_dwordx2 v[218:219], v[66:67], off offset:64
	global_load_dwordx2 v[220:221], v[66:67], off offset:80
	global_load_dwordx2 v[222:223], v[66:67], off offset:96
	global_load_dwordx2 v[224:225], v[66:67], off offset:112
	global_load_dwordx2 v[226:227], v[242:243], off
	global_load_dwordx2 v[228:229], v[242:243], off offset:16
	global_load_dwordx2 v[230:231], v[242:243], off offset:32
	global_load_dwordx2 v[232:233], v[242:243], off offset:48
	global_load_dwordx2 v[234:235], v[242:243], off offset:64
	global_load_dwordx2 v[236:237], v[242:243], off offset:80
	global_load_dwordx2 v[238:239], v[242:243], off offset:96
	global_load_dwordx2 v[240:241], v[242:243], off offset:112
	s_waitcnt vmcnt(0)
	v_mov_b32_e32 v72, v210
	v_mov_b32_e32 v73, v211
	v_and_b32_e32 v75, 0xffff0000, v73
	v_lshlrev_b32_e32 v74, 16, v73
	v_and_b32_e32 v73, 0xffff0000, v72
	v_lshlrev_b32_e32 v72, 16, v72
	v_pk_fma_f32 v[52:53], v[74:75], s[62:63], v[52:53] op_sel_hi:[1,0,1]
	v_pk_fma_f32 v[50:51], v[72:73], s[62:63], v[50:51] op_sel_hi:[1,0,1]
	s_nop 0
	v_cvt_pk_bf16_f32 v50, v50, v51
	v_cvt_pk_bf16_f32 v51, v52, v53
	global_store_dwordx2 v[66:67], v[50:51], off
	v_mov_b32_e32 v50, v212
	v_mov_b32_e32 v51, v213
	v_and_b32_e32 v53, 0xffff0000, v51
	v_lshlrev_b32_e32 v52, 16, v51
	v_and_b32_e32 v51, 0xffff0000, v50
	v_lshlrev_b32_e32 v50, 16, v50
	v_pk_fma_f32 v[52:53], v[52:53], s[62:63], v[56:57] op_sel_hi:[1,0,1]
	v_pk_fma_f32 v[50:51], v[50:51], s[62:63], v[54:55] op_sel_hi:[1,0,1]
	s_nop 0
	v_cvt_pk_bf16_f32 v50, v50, v51
	v_cvt_pk_bf16_f32 v51, v52, v53
	global_store_dwordx2 v[66:67], v[50:51], off offset:16
	v_mov_b32_e32 v50, v214
	v_mov_b32_e32 v51, v215
	v_and_b32_e32 v53, 0xffff0000, v51
	v_lshlrev_b32_e32 v52, 16, v51
	v_and_b32_e32 v51, 0xffff0000, v50
	v_lshlrev_b32_e32 v50, 16, v50
	v_pk_fma_f32 v[52:53], v[52:53], s[62:63], v[60:61] op_sel_hi:[1,0,1]
	v_pk_fma_f32 v[50:51], v[50:51], s[62:63], v[58:59] op_sel_hi:[1,0,1]
	s_nop 0
	v_cvt_pk_bf16_f32 v50, v50, v51
	v_cvt_pk_bf16_f32 v51, v52, v53
	global_store_dwordx2 v[66:67], v[50:51], off offset:32
	v_mov_b32_e32 v50, v216
	v_mov_b32_e32 v51, v217
	v_and_b32_e32 v53, 0xffff0000, v51
	v_lshlrev_b32_e32 v52, 16, v51
	v_and_b32_e32 v51, 0xffff0000, v50
	v_lshlrev_b32_e32 v50, 16, v50
	v_pk_fma_f32 v[52:53], v[52:53], s[62:63], v[64:65] op_sel_hi:[1,0,1]
	v_pk_fma_f32 v[50:51], v[50:51], s[62:63], v[62:63] op_sel_hi:[1,0,1]
	s_nop 0
	v_cvt_pk_bf16_f32 v50, v50, v51
	v_cvt_pk_bf16_f32 v51, v52, v53
	global_store_dwordx2 v[66:67], v[50:51], off offset:48
	v_or_b32_e32 v50, 32, v68
	v_ashrrev_i32_e32 v51, 31, v50
	v_lshlrev_b64 v[50:51], 11, v[50:51]
	v_lshl_add_u64 v[50:51], s[4:5], 0, v[50:51]
	v_lshl_add_u64 v[50:51], v[50:51], 0, v[70:71]
	v_mov_b32_e32 v52, v226
	v_mov_b32_e32 v53, v227
	v_and_b32_e32 v55, 0xffff0000, v53
	v_lshlrev_b32_e32 v54, 16, v53
	v_and_b32_e32 v53, 0xffff0000, v52
	v_lshlrev_b32_e32 v52, 16, v52
	v_pk_fma_f32 v[36:37], v[54:55], s[62:63], v[36:37] op_sel_hi:[1,0,1]
	v_pk_fma_f32 v[34:35], v[52:53], s[62:63], v[34:35] op_sel_hi:[1,0,1]
	s_nop 0
	v_cvt_pk_bf16_f32 v34, v34, v35
	v_cvt_pk_bf16_f32 v35, v36, v37
	global_store_dwordx2 v[50:51], v[34:35], off
	v_mov_b32_e32 v34, v228
	v_mov_b32_e32 v35, v229
	v_and_b32_e32 v37, 0xffff0000, v35
	v_lshlrev_b32_e32 v36, 16, v35
	v_and_b32_e32 v35, 0xffff0000, v34
	v_lshlrev_b32_e32 v34, 16, v34
	v_pk_fma_f32 v[36:37], v[36:37], s[62:63], v[40:41] op_sel_hi:[1,0,1]
	v_pk_fma_f32 v[34:35], v[34:35], s[62:63], v[38:39] op_sel_hi:[1,0,1]
	s_nop 0
	v_cvt_pk_bf16_f32 v34, v34, v35
	v_cvt_pk_bf16_f32 v35, v36, v37
	global_store_dwordx2 v[50:51], v[34:35], off offset:16
	v_mov_b32_e32 v34, v230
	v_mov_b32_e32 v35, v231
	v_and_b32_e32 v37, 0xffff0000, v35
	v_lshlrev_b32_e32 v36, 16, v35
	v_and_b32_e32 v35, 0xffff0000, v34
	v_lshlrev_b32_e32 v34, 16, v34
	v_pk_fma_f32 v[36:37], v[36:37], s[62:63], v[44:45] op_sel_hi:[1,0,1]
	v_pk_fma_f32 v[34:35], v[34:35], s[62:63], v[42:43] op_sel_hi:[1,0,1]
	s_nop 0
	v_cvt_pk_bf16_f32 v34, v34, v35
	v_cvt_pk_bf16_f32 v35, v36, v37
	global_store_dwordx2 v[50:51], v[34:35], off offset:32
	v_mov_b32_e32 v34, v232
	v_mov_b32_e32 v35, v233
	v_and_b32_e32 v37, 0xffff0000, v35
	v_lshlrev_b32_e32 v36, 16, v35
	v_and_b32_e32 v35, 0xffff0000, v34
	v_lshlrev_b32_e32 v34, 16, v34
	v_pk_fma_f32 v[36:37], v[36:37], s[62:63], v[48:49] op_sel_hi:[1,0,1]
	v_pk_fma_f32 v[34:35], v[34:35], s[62:63], v[46:47] op_sel_hi:[1,0,1]
	s_nop 0
	v_cvt_pk_bf16_f32 v34, v34, v35
	v_cvt_pk_bf16_f32 v35, v36, v37
	global_store_dwordx2 v[50:51], v[34:35], off offset:48
	v_mov_b32_e32 v34, v218
	v_mov_b32_e32 v35, v219
	v_and_b32_e32 v37, 0xffff0000, v35
	v_lshlrev_b32_e32 v36, 16, v35
	v_and_b32_e32 v35, 0xffff0000, v34
	v_lshlrev_b32_e32 v34, 16, v34
	v_pk_fma_f32 v[20:21], v[36:37], s[62:63], v[20:21] op_sel_hi:[1,0,1]
	v_pk_fma_f32 v[18:19], v[34:35], s[62:63], v[18:19] op_sel_hi:[1,0,1]
	s_nop 0
	v_cvt_pk_bf16_f32 v18, v18, v19
	v_cvt_pk_bf16_f32 v19, v20, v21
	global_store_dwordx2 v[66:67], v[18:19], off offset:64
	v_mov_b32_e32 v18, v220
	v_mov_b32_e32 v19, v221
	v_and_b32_e32 v21, 0xffff0000, v19
	v_lshlrev_b32_e32 v20, 16, v19
	v_and_b32_e32 v19, 0xffff0000, v18
	v_lshlrev_b32_e32 v18, 16, v18
	v_pk_fma_f32 v[20:21], v[20:21], s[62:63], v[24:25] op_sel_hi:[1,0,1]
	v_pk_fma_f32 v[18:19], v[18:19], s[62:63], v[22:23] op_sel_hi:[1,0,1]
	s_nop 0
	v_cvt_pk_bf16_f32 v18, v18, v19
	v_cvt_pk_bf16_f32 v19, v20, v21
	global_store_dwordx2 v[66:67], v[18:19], off offset:80
	v_mov_b32_e32 v18, v222
	v_mov_b32_e32 v19, v223
	v_and_b32_e32 v21, 0xffff0000, v19
	v_lshlrev_b32_e32 v20, 16, v19
	v_and_b32_e32 v19, 0xffff0000, v18
	v_lshlrev_b32_e32 v18, 16, v18
	v_pk_fma_f32 v[20:21], v[20:21], s[62:63], v[28:29] op_sel_hi:[1,0,1]
	v_pk_fma_f32 v[18:19], v[18:19], s[62:63], v[26:27] op_sel_hi:[1,0,1]
	s_nop 0
	v_cvt_pk_bf16_f32 v18, v18, v19
	v_cvt_pk_bf16_f32 v19, v20, v21
	global_store_dwordx2 v[66:67], v[18:19], off offset:96
	v_mov_b32_e32 v18, v224
	v_mov_b32_e32 v19, v225
	v_and_b32_e32 v21, 0xffff0000, v19
	v_lshlrev_b32_e32 v20, 16, v19
	v_and_b32_e32 v19, 0xffff0000, v18
	v_lshlrev_b32_e32 v18, 16, v18
	v_pk_fma_f32 v[20:21], v[20:21], s[62:63], v[32:33] op_sel_hi:[1,0,1]
	v_pk_fma_f32 v[18:19], v[18:19], s[62:63], v[30:31] op_sel_hi:[1,0,1]
	s_nop 0
	v_cvt_pk_bf16_f32 v18, v18, v19
	v_cvt_pk_bf16_f32 v19, v20, v21
	global_store_dwordx2 v[66:67], v[18:19], off offset:112
	v_mov_b32_e32 v18, v234
	v_mov_b32_e32 v19, v235
	v_and_b32_e32 v21, 0xffff0000, v19
	v_lshlrev_b32_e32 v20, 16, v19
	v_and_b32_e32 v19, 0xffff0000, v18
	v_lshlrev_b32_e32 v18, 16, v18
	v_pk_fma_f32 v[4:5], v[20:21], s[62:63], v[4:5] op_sel_hi:[1,0,1]
	v_pk_fma_f32 v[2:3], v[18:19], s[62:63], v[2:3] op_sel_hi:[1,0,1]
	s_nop 0
	v_cvt_pk_bf16_f32 v2, v2, v3
	v_cvt_pk_bf16_f32 v3, v4, v5
	global_store_dwordx2 v[50:51], v[2:3], off offset:64
	v_mov_b32_e32 v2, v236
	v_mov_b32_e32 v3, v237
	v_and_b32_e32 v5, 0xffff0000, v3
	v_lshlrev_b32_e32 v4, 16, v3
	v_and_b32_e32 v3, 0xffff0000, v2
	v_lshlrev_b32_e32 v2, 16, v2
	v_pk_fma_f32 v[4:5], v[4:5], s[62:63], v[8:9] op_sel_hi:[1,0,1]
	v_pk_fma_f32 v[2:3], v[2:3], s[62:63], v[6:7] op_sel_hi:[1,0,1]
	s_nop 0
	v_cvt_pk_bf16_f32 v2, v2, v3
	v_cvt_pk_bf16_f32 v3, v4, v5
	global_store_dwordx2 v[50:51], v[2:3], off offset:80
	v_mov_b32_e32 v2, v238
	v_mov_b32_e32 v3, v239
	v_and_b32_e32 v5, 0xffff0000, v3
	v_lshlrev_b32_e32 v4, 16, v3
	v_and_b32_e32 v3, 0xffff0000, v2
	v_lshlrev_b32_e32 v2, 16, v2
	v_pk_fma_f32 v[4:5], v[4:5], s[62:63], v[12:13] op_sel_hi:[1,0,1]
	v_pk_fma_f32 v[2:3], v[2:3], s[62:63], v[10:11] op_sel_hi:[1,0,1]
	s_nop 0
	v_cvt_pk_bf16_f32 v2, v2, v3
	v_cvt_pk_bf16_f32 v3, v4, v5
	global_store_dwordx2 v[50:51], v[2:3], off offset:96
	v_mov_b32_e32 v2, v240
	v_mov_b32_e32 v3, v241
	v_and_b32_e32 v5, 0xffff0000, v3
	v_lshlrev_b32_e32 v4, 16, v3
	v_and_b32_e32 v3, 0xffff0000, v2
	v_lshlrev_b32_e32 v2, 16, v2
	v_pk_fma_f32 v[4:5], v[4:5], s[62:63], v[16:17] op_sel_hi:[1,0,1]
	v_pk_fma_f32 v[2:3], v[2:3], s[62:63], v[14:15] op_sel_hi:[1,0,1]
	s_nop 0
	v_cvt_pk_bf16_f32 v2, v2, v3
	v_cvt_pk_bf16_f32 v3, v4, v5
	global_store_dwordx2 v[50:51], v[2:3], off offset:112
	s_branch .LBB0_544
